# P6 task top: g/beta loads issued first, then K and Q loads; top wait relaxed to vmcnt(24) and the K ladder by +9 so cumsum and KK^T overlap the K/Q transfers
# baseline (speedup 1.0000x reference)
.LBB0_686:
	s_and_b32 s4, s33, 63
	s_lshr_b32 s0, s33, 6
	s_ashr_i32 s20, s33, 11
	s_bfe_u32 s37, s0, 0x40001
	s_lshl_b32 s0, s20, 12
	v_writelane_b32 v250, s4, 13
	s_lshl_b32 s4, s4, 6
	v_mov_b32_e32 v126, v190
	s_or_b32 s0, s0, s4
	s_bfe_u32 s1, s33, 0x50006
	v_add_u32_e32 v2, s0, v126
	v_ashrrev_i32_e32 v3, 31, v2
	v_lshlrev_b64 v[2:3], 7, v[2:3]
	v_readlane_b32 s4, v251, 57
	v_lshl_or_b32 v2, s1, 2, v2
	v_readlane_b32 s5, v251, 58
	v_cmp_lt_i32_e32 vcc, 0, v126
	s_movk_i32 s1, 0x80
	v_lshl_add_u64 v[4:5], s[4:5], 0, v[2:3]
	global_load_dword v4, v[4:5], off
	v_readlane_b32 s4, v251, 59
	v_readlane_b32 s5, v251, 60
	v_readlane_b32 s6, v251, 55
	v_ashrrev_i32_e32 v127, 31, v126
	v_lshl_add_u64 v[2:3], s[4:5], 0, v[2:3]
	global_load_dword v193, v[2:3], off
	s_lshl_b32 s98, s37, 8
	v_readlane_b32 s96, v251, 61
	v_readlane_b32 s97, v251, 63
	v_and_b32_e32 v244, 31, v190
	v_lshrrev_b32_e32 v246, 5, v190
	s_add_u32 s96, s96, s98
	s_addc_u32 s97, s97, 0
	v_lshlrev_b32_e32 v246, 4, v246
	v_mov_b32_e32 v247, 0
	v_or_b32_e32 v244, s0, v244
	v_ashrrev_i32_e32 v245, 31, v244
	v_or_b32_e32 v248, 32, v244
	v_ashrrev_i32_e32 v249, 31, v248
	v_lshlrev_b64 v[244:245], 12, v[244:245]
	v_lshlrev_b64 v[248:249], 12, v[248:249]
	v_lshl_add_u64 v[244:245], v[244:245], 0, v[246:247]
	v_lshl_add_u64 v[248:249], v[248:249], 0, v[246:247]
	v_lshl_add_u64 v[246:247], v[244:245], 0, s[96:97]
	v_lshl_add_u64 v[248:249], v[248:249], 0, s[96:97]
	v_readlane_b32 s96, v250, 1
	v_readlane_b32 s97, v250, 2
	s_add_u32 s96, s96, s98
	s_addc_u32 s97, s97, 0
	s_nop 0
	v_lshl_add_u64 v[244:245], v[244:245], 0, s[96:97]
	global_load_dwordx4 v[50:53], v[246:247], off
	global_load_dwordx4 v[102:105], v[246:247], off offset:32
	global_load_dwordx4 v[94:97], v[246:247], off offset:64
	global_load_dwordx4 v[86:89], v[246:247], off offset:96
	global_load_dwordx4 v[78:81], v[246:247], off offset:128
	global_load_dwordx4 v[74:77], v[246:247], off offset:160
	global_load_dwordx4 v[70:73], v[246:247], off offset:192
	global_load_dwordx4 v[66:69], v[246:247], off offset:224
	global_load_dwordx4 v[54:57], v[248:249], off
	global_load_dwordx4 v[118:121], v[248:249], off offset:32
	global_load_dwordx4 v[114:117], v[248:249], off offset:64
	global_load_dwordx4 v[110:113], v[248:249], off offset:96
	global_load_dwordx4 v[106:109], v[248:249], off offset:128
	global_load_dwordx4 v[98:101], v[248:249], off offset:160
	global_load_dwordx4 v[90:93], v[248:249], off offset:192
	global_load_dwordx4 v[82:85], v[248:249], off offset:224
	global_load_dwordx4 v[228:231], v[244:245], off
	global_load_dwordx4 v[168:171], v[244:245], off offset:32
	global_load_dwordx4 v[176:179], v[244:245], off offset:64
	global_load_dwordx4 v[212:215], v[244:245], off offset:96
	global_load_dwordx4 v[216:219], v[244:245], off offset:128
	global_load_dwordx4 v[220:223], v[244:245], off offset:160
	global_load_dwordx4 v[236:239], v[244:245], off offset:192
	global_load_dwordx4 v[240:243], v[244:245], off offset:224
	v_lshlrev_b32_e32 v2, 2, v126
	v_add_u32_e32 v3, 0xfc, v2
	v_and_b32_e32 v3, 0xfc, v3
	s_add_u32 s4, s94, s7
	s_addc_u32 s5, s95, s8
	v_and_b32_e32 v192, 31, v126
	s_waitcnt vmcnt(24)
	v_ashrrev_i32_e32 v63, 5, v126
	v_lshlrev_b32_e32 v128, 3, v63
	v_ashrrev_i32_e32 v129, 31, v128
	v_lshl_add_u32 v62, v192, 2, s6
	v_writelane_b32 v250, s7, 15
	v_mov_b32_e32 v194, 0
	v_writelane_b32 v250, s8, 17
	ds_bpermute_b32 v3, v3, v4
	s_waitcnt lgkmcnt(0)
	v_cndmask_b32_e32 v3, 0, v3, vcc
	v_add_f32_e32 v3, v4, v3
	v_add_u32_e32 v4, 0xf8, v2
	v_and_b32_e32 v4, 0xfc, v4
	ds_bpermute_b32 v4, v4, v3
	v_cmp_lt_i32_e32 vcc, 1, v126
	s_waitcnt lgkmcnt(0)
	s_nop 0
	v_cndmask_b32_e32 v4, 0, v4, vcc
	v_add_f32_e32 v3, v3, v4
	v_add_u32_e32 v4, 0xf0, v2
	v_and_b32_e32 v4, 0xfc, v4
	ds_bpermute_b32 v4, v4, v3
	v_cmp_lt_i32_e32 vcc, 3, v126
	s_waitcnt lgkmcnt(0)
	s_nop 0
	v_cndmask_b32_e32 v4, 0, v4, vcc
	v_add_f32_e32 v3, v3, v4
	v_add_u32_e32 v4, 0xe0, v2
	v_and_b32_e32 v4, 0xfc, v4
	ds_bpermute_b32 v4, v4, v3
	v_cmp_lt_i32_e32 vcc, 7, v126
	s_waitcnt lgkmcnt(0)
	s_nop 0
	v_cndmask_b32_e32 v4, 0, v4, vcc
	v_add_f32_e32 v3, v3, v4
	v_add_u32_e32 v4, 0xc0, v2
	v_and_b32_e32 v4, 0xfc, v4
	ds_bpermute_b32 v4, v4, v3
	v_cmp_lt_i32_e32 vcc, 15, v126
	s_waitcnt lgkmcnt(0)
	s_nop 0
	v_cndmask_b32_e32 v4, 0, v4, vcc
	v_add_f32_e32 v3, v3, v4
	v_bitop3_b32 v4, v2, s1, v191 bitop3:0x6c
	ds_bpermute_b32 v4, v4, v3
	v_cmp_lt_i32_e32 vcc, 31, v126
	v_add_u32_e32 v2, s6, v2
	v_readlane_b32 s1, v251, 61
	s_waitcnt lgkmcnt(0)
	v_cndmask_b32_e32 v4, 0, v4, vcc
	v_add_f32_e32 v166, v3, v4
	ds_write2st64_b32 v2, v166, v193 offset1:1
	v_lshl_add_u64 v[2:3], v[126:127], 2, s[4:5]
	global_store_dword v[2:3], v166, off
	v_or_b32_e32 v2, s0, v192
	s_lshl_b32 s0, s37, 8
	v_ashrrev_i32_e32 v3, 31, v2
	s_add_u32 s0, s1, s0
	v_readlane_b32 s1, v251, 63
	v_lshlrev_b64 v[60:61], 12, v[2:3]
	v_or_b32_e32 v2, 32, v2
	s_addc_u32 s1, s1, 0
	v_ashrrev_i32_e32 v3, 31, v2
	v_lshl_add_u64 v[4:5], v[128:129], 1, s[0:1]
	v_lshlrev_b64 v[58:59], 12, v[2:3]
	s_waitcnt lgkmcnt(0)
	v_lshl_add_u64 v[6:7], v[4:5], 0, v[60:61]
	v_lshl_add_u64 v[2:3], v[4:5], 0, v[58:59]
	v_lshl_add_u32 v127, v63, 4, s6
	ds_read2_b32 v[130:131], v62 offset1:32
	ds_read2_b32 v[132:133], v127 offset0:32 offset1:96
	v_lshlrev_b32_e32 v62, 2, v63
	v_cmp_ge_i32_e64 s[86:87], v192, v62
	v_cmp_lt_i32_e64 s[0:1], v192, v62
	s_waitcnt vmcnt(24)
	v_mfma_f32_32x32x16_bf16 v[34:49], v[50:53], v[50:53], 0
	s_waitcnt vmcnt(16)
	v_mfma_f32_32x32x16_bf16 v[18:33], v[54:57], v[50:53], 0
	v_mfma_f32_32x32x16_bf16 v[2:17], v[54:57], v[54:57], 0
	v_mfma_f32_32x32x16_bf16 v[34:49], v[102:105], v[102:105], v[34:49]
	s_waitcnt vmcnt(15)
	v_mfma_f32_32x32x16_bf16 v[18:33], v[118:121], v[102:105], v[18:33]
	v_mfma_f32_32x32x16_bf16 v[2:17], v[118:121], v[118:121], v[2:17]
	v_mfma_f32_32x32x16_bf16 v[34:49], v[94:97], v[94:97], v[34:49]
	s_waitcnt vmcnt(14)
	v_mfma_f32_32x32x16_bf16 v[18:33], v[114:117], v[94:97], v[18:33]
	v_mfma_f32_32x32x16_bf16 v[2:17], v[114:117], v[114:117], v[2:17]
	v_mfma_f32_32x32x16_bf16 v[34:49], v[86:89], v[86:89], v[34:49]
	s_waitcnt vmcnt(13)
	v_mfma_f32_32x32x16_bf16 v[18:33], v[110:113], v[86:89], v[18:33]
	v_mfma_f32_32x32x16_bf16 v[2:17], v[110:113], v[110:113], v[2:17]
	v_mfma_f32_32x32x16_bf16 v[34:49], v[78:81], v[78:81], v[34:49]
	s_waitcnt vmcnt(12)
	v_mfma_f32_32x32x16_bf16 v[18:33], v[106:109], v[78:81], v[18:33]
	v_mfma_f32_32x32x16_bf16 v[2:17], v[106:109], v[106:109], v[2:17]
	v_mfma_f32_32x32x16_bf16 v[34:49], v[74:77], v[74:77], v[34:49]
	s_waitcnt vmcnt(11)
	v_mfma_f32_32x32x16_bf16 v[18:33], v[98:101], v[74:77], v[18:33]
	v_mfma_f32_32x32x16_bf16 v[2:17], v[98:101], v[98:101], v[2:17]
	v_mfma_f32_32x32x16_bf16 v[34:49], v[70:73], v[70:73], v[34:49]
	s_waitcnt vmcnt(10)
	v_mfma_f32_32x32x16_bf16 v[18:33], v[90:93], v[70:73], v[18:33]
	v_mfma_f32_32x32x16_bf16 v[2:17], v[90:93], v[90:93], v[2:17]
	v_mfma_f32_32x32x16_bf16 v[34:49], v[66:69], v[66:69], v[34:49]
	s_waitcnt vmcnt(9)
	v_mfma_f32_32x32x16_bf16 v[18:33], v[82:85], v[66:69], v[18:33]
	v_mfma_f32_32x32x16_bf16 v[2:17], v[82:85], v[82:85], v[2:17]
	s_and_saveexec_b64 s[4:5], s[0:1]
	s_cbranch_execz .LBB0_688
	ds_read2st64_b32 v[64:65], v127 offset1:1
	s_waitcnt lgkmcnt(0)
	v_sub_f32_e32 v63, v64, v130
	v_mul_f32_e32 v63, 0x3fb8aa3b, v63
	v_exp_f32_e32 v63, v63
	s_nop 1
	v_mul_f32_e32 v34, v34, v65
	v_mul_f32_e32 v194, v34, v63
